# scan: waves 0-3 complete the y-output FLUSH after their PREP quarter (no up-front LDS wait)
# baseline (speedup 1.0000x reference)
.Lsx0_c:
	v_mov_b32_e32 v22, 0
	v_mov_b32_e32 v23, 0
	v_mov_b32_e32 v24, 0
	v_mov_b32_e32 v25, 0
	s_and_saveexec_b64 s[2:3], s[56:57]
	s_cbranch_execz .LBB0_403
	ds_read_b128 v[48:51], v174
	ds_read_b128 v[60:63], v192 offset:49152
	ds_read_b128 v[52:55], v174 offset:64
	ds_read_b128 v[64:67], v192 offset:49216
	ds_read_b128 v[56:59], v175
	ds_read_b128 v[68:71], v199
	ds_read_b128 v[72:75], v192 offset:58368
	ds_read_b128 v[76:79], v192 offset:58432
	ds_read_b128 v[80:83], v151
	ds_read_b128 v[84:87], v151 offset:16
	ds_read_b128 v[88:91], v151 offset:32
	ds_read_b128 v[92:95], v151 offset:48
	s_waitcnt lgkmcnt(10)
	v_mfma_f32_16x16x32_bf16 v[30:33], v[48:51], v[60:63], 0
	s_waitcnt lgkmcnt(8)
	v_mfma_f32_16x16x32_bf16 v[30:33], v[52:55], v[64:67], v[30:33]
	s_waitcnt lgkmcnt(6)
	v_mfma_f32_16x16x32_bf16 v[30:33], v[56:59], v[68:71], v[30:33]
	s_waitcnt lgkmcnt(5)
	v_mfma_f32_16x16x32_bf16 v[22:25], v[48:51], v[72:75], 0
	s_waitcnt lgkmcnt(4)
	v_mfma_f32_16x16x32_bf16 v[22:25], v[52:55], v[76:79], v[22:25]
	s_cmp_eq_u32 s36, 0
	s_cbranch_scc1 .Lis0b
	s_cmp_gt_u32 s36, 62
	s_cbranch_scc1 .Lis0b
	s_add_i32 s24, s19, 0xffffffc0
	s_add_i32 s25, s21, 0x30
	s_and_b64 s[98:99], s[12:13], exec
	s_cselect_b32 s24, s25, s24
	v_lshl_add_u32 v194, s24, 6, v183
	v_lshlrev_b32_e32 v112, 1, v194
	global_load_dword v5, v112, s[44:45]
	global_load_dword v207, v112, s[44:45] offset:-1024
	global_load_dword v6, v112, s[42:43]
	global_load_dword v208, v112, s[42:43] offset:-1024
	global_load_dword v7, v112, s[0:1]
	global_load_dword v209, v112, s[0:1] offset:-1024
	global_load_dword v8, v112, s[34:35]
	global_load_dword v210, v112, s[34:35] offset:-1024
	global_load_dword v9, v112, s[76:77]
	global_load_dword v211, v112, s[76:77] offset:-1024
	v_add_u32_e32 v194, s24, v184
	v_lshlrev_b32_e32 v114, 2, v194
	global_load_dword v110, v114, s[40:41]
	global_load_dword v212, v114, s[40:41] offset:-32

.Lpq0_end:
	s_waitcnt lgkmcnt(0)
	s_and_b64 s[98:99], s[54:55], exec
	s_cbranch_scc0 .Lfl0
	s_cmp_lg_u32 s21, 0
	s_cbranch_scc0 .Lfl0
	v_cvt_pk_bf16_f32 v240, v236, v237
	global_store_dword v[238:239], v240, off
.Lfl0:
	s_barrier
	v_add_u32_e32 v200, v146, v145
	v_add_u32_e32 v112, v156, v163
	ds_read_b128 v[48:51], v180
	ds_read_b128 v[52:55], v112 offset:62976
	ds_read_b128 v[56:59], v112 offset:64256
	v_sub_u32_e32 v113, v164, v143
	v_mad_u32_u24 v113, v145, 5, v113
	v_add_u32_e32 v113, 0x18d00, v113
	ds_read_b128 v[88:91], v113
	ds_read_b128 v[92:95], v113 offset:64
	s_and_b64 s[98:99], s[56:57], exec
	s_cbranch_scc0 .Lcp0
	s_cmp_gt_u32 s36, 62
	s_cbranch_scc1 .Lcp0
	s_cmp_eq_u32 s36, 0
	s_cbranch_scc1 .Lvw0
	s_waitcnt vmcnt(14)
	s_branch .Lvx0

.Lsx1_c:
	v_mov_b32_e32 v22, 0
	v_mov_b32_e32 v23, 0
	v_mov_b32_e32 v24, 0
	v_mov_b32_e32 v25, 0
	s_and_saveexec_b64 s[74:75], s[56:57]
	s_cbranch_execz .LBB0_432
	ds_read_b128 v[48:51], v174
	ds_read_b128 v[60:63], v192 offset:51456
	ds_read_b128 v[52:55], v174 offset:64
	ds_read_b128 v[64:67], v192 offset:51520
	ds_read_b128 v[56:59], v175 offset:5120
	ds_read_b128 v[68:71], v199
	ds_read_b128 v[72:75], v192 offset:60672
	ds_read_b128 v[76:79], v192 offset:60736
	ds_read_b128 v[80:83], v151
	ds_read_b128 v[84:87], v151 offset:16
	ds_read_b128 v[88:91], v151 offset:32
	ds_read_b128 v[92:95], v151 offset:48
	s_waitcnt lgkmcnt(10)
	v_mfma_f32_16x16x32_bf16 v[30:33], v[48:51], v[60:63], 0
	s_waitcnt lgkmcnt(8)
	v_mfma_f32_16x16x32_bf16 v[30:33], v[52:55], v[64:67], v[30:33]
	s_waitcnt lgkmcnt(6)
	v_mfma_f32_16x16x32_bf16 v[30:33], v[56:59], v[68:71], v[30:33]
	s_waitcnt lgkmcnt(5)
	v_mfma_f32_16x16x32_bf16 v[22:25], v[48:51], v[72:75], 0
	s_waitcnt lgkmcnt(4)
	v_mfma_f32_16x16x32_bf16 v[22:25], v[52:55], v[76:79], v[22:25]
	s_cmp_gt_u32 s36, 61
	s_cbranch_scc1 .Lis1bw
	s_add_i32 s24, s19, 0xffffffb0
	s_add_i32 s25, s21, 64
	s_and_b64 s[98:99], s[12:13], exec
	s_cselect_b32 s24, s25, s24
	v_lshl_add_u32 v194, s24, 6, v183
	v_lshlrev_b32_e32 v112, 1, v194
	global_load_dword v0, v112, s[44:45]
	global_load_dword v201, v112, s[44:45] offset:-1024
	global_load_dword v1, v112, s[42:43]
	global_load_dword v202, v112, s[42:43] offset:-1024
	global_load_dword v2, v112, s[0:1]
	global_load_dword v203, v112, s[0:1] offset:-1024
	global_load_dword v4, v112, s[76:77]
	global_load_dword v205, v112, s[76:77] offset:-1024
	global_load_dword v3, v112, s[34:35]
	global_load_dword v204, v112, s[34:35] offset:-1024
	v_add_u32_e32 v194, s24, v184
	v_lshlrev_b32_e32 v114, 2, v194
	global_load_dword v108, v114, s[40:41]
	global_load_dword v206, v114, s[40:41] offset:-32
	s_branch .Lis1b

.Lpq1_end:
	s_waitcnt lgkmcnt(0)
	s_and_b64 s[98:99], s[54:55], exec
	s_cbranch_scc0 .Lfl1
	v_cvt_pk_bf16_f32 v240, v236, v237
	global_store_dword v[238:239], v240, off
.Lfl1:
	s_barrier
	s_and_b64 s[24:25], s[46:47], s[2:3]
	ds_read_b128 v[48:51], v180 offset:5120
	ds_read_b128 v[52:55], v170 offset:5120
	ds_read_b128 v[56:59], v170 offset:6400
	v_sub_u32_e32 v113, v164, v143
	v_mad_u32_u24 v113, v145, 5, v113
	v_add_u32_e32 v113, 0x18e00, v113
	ds_read_b128 v[88:91], v113
	ds_read_b128 v[92:95], v113 offset:64
	s_and_b64 s[98:99], s[56:57], exec
	s_cbranch_scc0 .Lcp1
	s_cmp_gt_u32 s36, 62
	s_cbranch_scc1 .Lcp1
	s_cmp_eq_u32 s36, 0
	s_cbranch_scc1 .Lvw1
	s_cmp_gt_u32 s36, 61
	s_cbranch_scc1 .Lvw1
	s_waitcnt vmcnt(14)
	s_branch .Lvx1
